# swa_finalize prologue: the low-rank gate weights and biases are staged into LDS with 16 loads in flight per iteration instead of one pair per round trip
# baseline (speedup 1.0000x reference)
; DI void swa_finalize(const P& p, char* smem, int vb, int nvb) {
;     ...
;   float* w2s = (float*)smem;
;   float* gbs = w2s + 8192;
;   float* sds = gbs + 512 + wave * 32;
;   __syncthreads();
;   for (int i = tid_; i < 8192; i += NTHR) w2s[i] = p.od_w2[i];
;   for (int i = tid_; i < 512; i += NTHR) gbs[i] = p.od_gb[i];
;   __syncthreads();
.LBB0_576:
	v_mov_b32_e32 v26, v18
	v_ashrrev_i32_e32 v27, 31, v26
	v_lshl_add_u64 v[26:27], v[26:27], 2, s[86:87]
	global_load_dword v224, v[26:27], off
	v_mov_b32_e32 v26, v19
	v_ashrrev_i32_e32 v27, 31, v26
	v_lshl_add_u64 v[26:27], v[26:27], 2, s[86:87]
	global_load_dword v225, v[26:27], off
	v_add_u32_e32 v26, 0x200, v18
	v_ashrrev_i32_e32 v27, 31, v26
	v_lshl_add_u64 v[26:27], v[26:27], 2, s[86:87]
	global_load_dword v226, v[26:27], off
	v_add_u32_e32 v26, 0x200, v19
	v_ashrrev_i32_e32 v27, 31, v26
	v_lshl_add_u64 v[26:27], v[26:27], 2, s[86:87]
	global_load_dword v227, v[26:27], off
	v_add_u32_e32 v26, 0x400, v18
	v_ashrrev_i32_e32 v27, 31, v26
	v_lshl_add_u64 v[26:27], v[26:27], 2, s[86:87]
	global_load_dword v228, v[26:27], off
	v_add_u32_e32 v26, 0x400, v19
	v_ashrrev_i32_e32 v27, 31, v26
	v_lshl_add_u64 v[26:27], v[26:27], 2, s[86:87]
	global_load_dword v229, v[26:27], off
	v_add_u32_e32 v26, 0x600, v18
	v_ashrrev_i32_e32 v27, 31, v26
	v_lshl_add_u64 v[26:27], v[26:27], 2, s[86:87]
	global_load_dword v230, v[26:27], off
	v_add_u32_e32 v26, 0x600, v19
	v_ashrrev_i32_e32 v27, 31, v26
	v_lshl_add_u64 v[26:27], v[26:27], 2, s[86:87]
	global_load_dword v231, v[26:27], off
	v_add_u32_e32 v26, 0x800, v18
	v_ashrrev_i32_e32 v27, 31, v26
	v_lshl_add_u64 v[26:27], v[26:27], 2, s[86:87]
	global_load_dword v232, v[26:27], off
	v_add_u32_e32 v26, 0x800, v19
	v_ashrrev_i32_e32 v27, 31, v26
	v_lshl_add_u64 v[26:27], v[26:27], 2, s[86:87]
	global_load_dword v233, v[26:27], off
	v_add_u32_e32 v26, 0xa00, v18
	v_ashrrev_i32_e32 v27, 31, v26
	v_lshl_add_u64 v[26:27], v[26:27], 2, s[86:87]
	global_load_dword v234, v[26:27], off
	v_add_u32_e32 v26, 0xa00, v19
	v_ashrrev_i32_e32 v27, 31, v26
	v_lshl_add_u64 v[26:27], v[26:27], 2, s[86:87]
	global_load_dword v235, v[26:27], off
	v_add_u32_e32 v26, 0xc00, v18
	v_ashrrev_i32_e32 v27, 31, v26
	v_lshl_add_u64 v[26:27], v[26:27], 2, s[86:87]
	global_load_dword v236, v[26:27], off
	v_add_u32_e32 v26, 0xc00, v19
	v_ashrrev_i32_e32 v27, 31, v26
	v_lshl_add_u64 v[26:27], v[26:27], 2, s[86:87]
	global_load_dword v237, v[26:27], off
	v_add_u32_e32 v26, 0xe00, v18
	v_ashrrev_i32_e32 v27, 31, v26
	v_lshl_add_u64 v[26:27], v[26:27], 2, s[86:87]
	global_load_dword v238, v[26:27], off
	v_add_u32_e32 v26, 0xe00, v19
	v_ashrrev_i32_e32 v27, 31, v26
	v_lshl_add_u64 v[26:27], v[26:27], 2, s[86:87]
	global_load_dword v239, v[26:27], off
	v_add_u32_e32 v23, -8, v23
	s_add_i32 s15, s15, 16
	v_cmp_eq_u32_e32 vcc, 0, v23
	s_or_b64 s[40:41], vcc, s[40:41]
	v_add_u32_e32 v19, 0x1000, v19
	v_add_u32_e32 v18, 0x1000, v18
	s_waitcnt vmcnt(14)
	ds_write2st64_b32 v24, v224, v225 offset1:4
	s_waitcnt vmcnt(12)
	ds_write2st64_b32 v24, v226, v227 offset0:8 offset1:12
	s_waitcnt vmcnt(10)
	ds_write2st64_b32 v24, v228, v229 offset0:16 offset1:20
	s_waitcnt vmcnt(8)
	ds_write2st64_b32 v24, v230, v231 offset0:24 offset1:28
	s_waitcnt vmcnt(6)
	ds_write2st64_b32 v24, v232, v233 offset0:32 offset1:36
	s_waitcnt vmcnt(4)
	ds_write2st64_b32 v24, v234, v235 offset0:40 offset1:44
	s_waitcnt vmcnt(2)
	ds_write2st64_b32 v24, v236, v237 offset0:48 offset1:52
	s_waitcnt vmcnt(0)
	ds_write2st64_b32 v24, v238, v239 offset0:56 offset1:60
	v_add_u32_e32 v24, 0x4000, v24
	v_mov_b32_e32 v25, s15
	s_andn2_b64 exec, exec, s[40:41]
	s_cbranch_execnz .LBB0_576
	s_or_b64 exec, exec, s[40:41]

; DI void swa_finalize(const P& p, char* smem, int vb, int nvb) {
;     ...
;   float* w2s = (float*)smem;
;   float* gbs = w2s + 8192;
;   float* sds = gbs + 512 + wave * 32;
;   __syncthreads();
;   for (int i = tid_; i < 8192; i += NTHR) w2s[i] = p.od_w2[i];
;   for (int i = tid_; i < 512; i += NTHR) gbs[i] = p.od_gb[i];
;   __syncthreads();
.LBB0_589:
	v_mov_b32_e32 v26, v18
	v_ashrrev_i32_e32 v27, 31, v26
	v_lshl_add_u64 v[26:27], v[26:27], 2, s[56:57]
	global_load_dword v224, v[26:27], off
	v_mov_b32_e32 v26, v19
	v_ashrrev_i32_e32 v27, 31, v26
	v_lshl_add_u64 v[26:27], v[26:27], 2, s[56:57]
	global_load_dword v225, v[26:27], off
	v_add_u32_e32 v26, 0x200, v18
	v_ashrrev_i32_e32 v27, 31, v26
	v_lshl_add_u64 v[26:27], v[26:27], 2, s[56:57]
	global_load_dword v226, v[26:27], off
	v_add_u32_e32 v26, 0x200, v19
	v_ashrrev_i32_e32 v27, 31, v26
	v_lshl_add_u64 v[26:27], v[26:27], 2, s[56:57]
	global_load_dword v227, v[26:27], off
	v_add_u32_e32 v26, 0x400, v18
	v_ashrrev_i32_e32 v27, 31, v26
	v_lshl_add_u64 v[26:27], v[26:27], 2, s[56:57]
	global_load_dword v228, v[26:27], off
	v_add_u32_e32 v26, 0x400, v19
	v_ashrrev_i32_e32 v27, 31, v26
	v_lshl_add_u64 v[26:27], v[26:27], 2, s[56:57]
	global_load_dword v229, v[26:27], off
	v_add_u32_e32 v26, 0x600, v18
	v_ashrrev_i32_e32 v27, 31, v26
	v_lshl_add_u64 v[26:27], v[26:27], 2, s[56:57]
	global_load_dword v230, v[26:27], off
	v_add_u32_e32 v26, 0x600, v19
	v_ashrrev_i32_e32 v27, 31, v26
	v_lshl_add_u64 v[26:27], v[26:27], 2, s[56:57]
	global_load_dword v231, v[26:27], off
	v_add_u32_e32 v26, 0x800, v18
	v_ashrrev_i32_e32 v27, 31, v26
	v_lshl_add_u64 v[26:27], v[26:27], 2, s[56:57]
	global_load_dword v232, v[26:27], off
	v_add_u32_e32 v26, 0x800, v19
	v_ashrrev_i32_e32 v27, 31, v26
	v_lshl_add_u64 v[26:27], v[26:27], 2, s[56:57]
	global_load_dword v233, v[26:27], off
	v_add_u32_e32 v26, 0xa00, v18
	v_ashrrev_i32_e32 v27, 31, v26
	v_lshl_add_u64 v[26:27], v[26:27], 2, s[56:57]
	global_load_dword v234, v[26:27], off
	v_add_u32_e32 v26, 0xa00, v19
	v_ashrrev_i32_e32 v27, 31, v26
	v_lshl_add_u64 v[26:27], v[26:27], 2, s[56:57]
	global_load_dword v235, v[26:27], off
	v_add_u32_e32 v26, 0xc00, v18
	v_ashrrev_i32_e32 v27, 31, v26
	v_lshl_add_u64 v[26:27], v[26:27], 2, s[56:57]
	global_load_dword v236, v[26:27], off
	v_add_u32_e32 v26, 0xc00, v19
	v_ashrrev_i32_e32 v27, 31, v26
	v_lshl_add_u64 v[26:27], v[26:27], 2, s[56:57]
	global_load_dword v237, v[26:27], off
	v_add_u32_e32 v26, 0xe00, v18
	v_ashrrev_i32_e32 v27, 31, v26
	v_lshl_add_u64 v[26:27], v[26:27], 2, s[56:57]
	global_load_dword v238, v[26:27], off
	v_add_u32_e32 v26, 0xe00, v19
	v_ashrrev_i32_e32 v27, 31, v26
	v_lshl_add_u64 v[26:27], v[26:27], 2, s[56:57]
	global_load_dword v239, v[26:27], off
	v_add_u32_e32 v23, -8, v23
	s_add_i32 s15, s15, 16
	v_cmp_eq_u32_e32 vcc, 0, v23
	s_or_b64 s[40:41], vcc, s[40:41]
	v_add_u32_e32 v19, 0x1000, v19
	v_add_u32_e32 v18, 0x1000, v18
	s_waitcnt vmcnt(14)
	ds_write2st64_b32 v24, v224, v225 offset1:4
	s_waitcnt vmcnt(12)
	ds_write2st64_b32 v24, v226, v227 offset0:8 offset1:12
	s_waitcnt vmcnt(10)
	ds_write2st64_b32 v24, v228, v229 offset0:16 offset1:20
	s_waitcnt vmcnt(8)
	ds_write2st64_b32 v24, v230, v231 offset0:24 offset1:28
	s_waitcnt vmcnt(6)
	ds_write2st64_b32 v24, v232, v233 offset0:32 offset1:36
	s_waitcnt vmcnt(4)
	ds_write2st64_b32 v24, v234, v235 offset0:40 offset1:44
	s_waitcnt vmcnt(2)
	ds_write2st64_b32 v24, v236, v237 offset0:48 offset1:52
	s_waitcnt vmcnt(0)
	ds_write2st64_b32 v24, v238, v239 offset0:56 offset1:60
	v_add_u32_e32 v24, 0x4000, v24
	v_mov_b32_e32 v25, s15
	s_andn2_b64 exec, exec, s[40:41]
	s_cbranch_execnz .LBB0_589
	s_or_b64 exec, exec, s[40:41]
